# scan inner loops unrolled x2 (4 steps per back-edge)
# speedup vs baseline: 1.0150x; 1.0090x over previous
.LBB0_859:
	s_waitcnt lgkmcnt(0)
	v_mov_b32_e32 v95, v96
	v_add_u32_e32 v96, s7, v100
	ds_read_b128 v[70:73], v96 offset:1568
	ds_read_b128 v[66:69], v96 offset:1584
	ds_read_b128 v[50:53], v96 offset:1824
	ds_read_b128 v[46:49], v96 offset:1840
	ds_read_b128 v[54:57], v96 offset:2080
	ds_read_b128 v[42:45], v96 offset:2096
	ds_read_b128 v[78:81], v96 offset:2336
	ds_read_b128 v[74:77], v96 offset:2352
	ds_read_b128 v[62:65], v96 offset:2592
	ds_read_b128 v[58:61], v96 offset:2608
	v_pk_fma_f32 v[34:35], v[84:85], v[34:35], 0 op_sel_hi:[1,1,0]
	v_pk_fma_f32 v[22:23], v[84:85], v[22:23], 0 op_sel_hi:[1,1,0]
	v_pk_fma_f32 v[34:35], v[86:87], v[36:37], v[34:35]
	v_pk_fma_f32 v[22:23], v[86:87], v[24:25], v[22:23]
	v_add_u32_e32 v103, s7, v102
	v_mov_b32_e32 v98, s7
	v_pk_fma_f32 v[24:25], v[88:89], v[38:39], v[34:35]
	v_pk_fma_f32 v[18:19], v[88:89], v[18:19], v[22:23]
	ds_read_b32 v0, v103 offset:2848
	ds_read_b64 v[98:99], v98 offset:3104
	v_pk_fma_f32 v[22:23], v[90:91], v[40:41], v[24:25]
	v_pk_fma_f32 v[20:21], v[90:91], v[20:21], v[18:19]
	v_add_f32_e32 v18, v22, v23
	v_add_f32_e32 v19, v20, v21
	s_nop 0
	v_add_f32_dpp v18, v18, v18 quad_perm:[1,0,3,2] row_mask:0xf bank_mask:0xf bound_ctrl:1
	v_add_f32_dpp v19, v19, v19 quad_perm:[1,0,3,2] row_mask:0xf bank_mask:0xf bound_ctrl:1
	s_nop 0
	v_add_f32_dpp v18, v18, v18 quad_perm:[2,3,0,1] row_mask:0xf bank_mask:0xf bound_ctrl:1
	v_add_f32_dpp v19, v19, v19 quad_perm:[2,3,0,1] row_mask:0xf bank_mask:0xf bound_ctrl:1
	s_nop 0
	v_add_f32_dpp v18, v18, v18 row_half_mirror row_mask:0xf bank_mask:0xf bound_ctrl:1
	v_mov_b32_e32 v22, v97
	v_mov_b32_e32 v23, v18
	v_pk_mul_f32 v[22:23], v[22:23], v[94:95]
	v_add_f32_dpp v19, v19, v19 row_half_mirror row_mask:0xf bank_mask:0xf bound_ctrl:1
	v_add_f32_e32 v19, v23, v19
	v_add_f32_e32 v19, v22, v19
	s_ashr_i32 s47, s46, 31
	v_bfe_u32 v20, v19, 16, 1
	s_lshl_b64 s[20:21], s[46:47], 9
	v_add3_u32 v19, v19, v20, s28
	v_lshl_add_u64 v[20:21], v[92:93], 0, s[20:21]
	global_store_short_d16_hi v[20:21], v19, off
	v_pk_mul_f32 v[2:3], v[84:85], v[2:3]
	s_nop 0
	v_pk_fma_f32 v[2:3], v[18:19], v[26:27], v[2:3] op_sel_hi:[0,1,1]
	v_pk_fma_f32 v[84:85], v[94:95], v[10:11], v[2:3] op_sel_hi:[0,1,1]
	v_pk_mul_f32 v[2:3], v[86:87], v[4:5]
	s_waitcnt lgkmcnt(5)
	v_pk_fma_f32 v[78:79], v[84:85], v[78:79], 0 op_sel_hi:[1,1,0]
	v_pk_fma_f32 v[2:3], v[18:19], v[28:29], v[2:3] op_sel_hi:[0,1,1]
	v_pk_fma_f32 v[86:87], v[94:95], v[12:13], v[2:3] op_sel_hi:[0,1,1]
	v_pk_mul_f32 v[2:3], v[88:89], v[6:7]
	v_pk_fma_f32 v[70:71], v[84:85], v[70:71], 0 op_sel_hi:[1,1,0]
	v_pk_fma_f32 v[2:3], v[18:19], v[30:31], v[2:3] op_sel_hi:[0,1,1]
	v_pk_fma_f32 v[88:89], v[94:95], v[14:15], v[2:3] op_sel_hi:[0,1,1]
	v_pk_mul_f32 v[2:3], v[90:91], v[8:9]
	v_pk_fma_f32 v[78:79], v[86:87], v[80:81], v[78:79]
	v_pk_fma_f32 v[2:3], v[18:19], v[32:33], v[2:3] op_sel_hi:[0,1,1]
	v_pk_fma_f32 v[90:91], v[94:95], v[16:17], v[2:3] op_sel_hi:[0,1,1]
	ds_read_b128 v[22:25], v96 offset:3136
	ds_read_b128 v[18:21], v96 offset:3152
	ds_read_b128 v[2:5], v96 offset:3392
	ds_read_b128 v[6:9], v96 offset:3408
	ds_read_b128 v[10:13], v96 offset:3648
	ds_read_b128 v[14:17], v96 offset:3664
	ds_read_b128 v[34:37], v96 offset:3904
	ds_read_b128 v[38:41], v96 offset:3920
	ds_read_b128 v[26:29], v96 offset:4160
	ds_read_b128 v[30:33], v96 offset:4176
	v_pk_fma_f32 v[70:71], v[86:87], v[72:73], v[70:71]
	s_waitcnt lgkmcnt(14)
	v_pk_fma_f32 v[72:73], v[88:89], v[74:75], v[78:79]
	v_pk_fma_f32 v[66:67], v[88:89], v[66:67], v[70:71]
	v_mov_b32_e32 v95, s7
	ds_read_b32 v94, v103 offset:4416
	ds_read_b64 v[96:97], v95 offset:4672
	v_pk_fma_f32 v[70:71], v[90:91], v[76:77], v[72:73]
	v_pk_fma_f32 v[68:69], v[90:91], v[68:69], v[66:67]
	v_add_f32_e32 v66, v70, v71
	v_add_f32_e32 v67, v68, v69
	s_nop 0
	v_add_f32_dpp v66, v66, v66 quad_perm:[1,0,3,2] row_mask:0xf bank_mask:0xf bound_ctrl:1
	v_add_f32_dpp v67, v67, v67 quad_perm:[1,0,3,2] row_mask:0xf bank_mask:0xf bound_ctrl:1
	s_nop 0
	v_add_f32_dpp v66, v66, v66 quad_perm:[2,3,0,1] row_mask:0xf bank_mask:0xf bound_ctrl:1
	v_add_f32_dpp v68, v67, v67 quad_perm:[2,3,0,1] row_mask:0xf bank_mask:0xf bound_ctrl:1
	s_nop 0
	v_add_f32_dpp v66, v66, v66 row_half_mirror row_mask:0xf bank_mask:0xf bound_ctrl:1
	s_waitcnt lgkmcnt(13)
	v_mov_b32_e32 v67, v0
	s_waitcnt lgkmcnt(12)
	v_pk_mul_f32 v[70:71], v[98:99], v[66:67]
	v_add_f32_dpp v67, v68, v68 row_half_mirror row_mask:0xf bank_mask:0xf bound_ctrl:1
	v_add_f32_e32 v67, v70, v67
	s_add_i32 s20, s2, s46
	v_add_f32_e32 v67, v71, v67
	s_ashr_i32 s21, s20, 31
	v_bfe_u32 v68, v67, 16, 1
	s_lshl_b64 s[20:21], s[20:21], 9
	v_add3_u32 v67, v67, v68, s28
	v_lshl_add_u64 v[68:69], v[92:93], 0, s[20:21]
	global_store_short_d16_hi v[68:69], v67, off
	v_pk_mul_f32 v[50:51], v[50:51], v[84:85]
	v_pk_mul_f32 v[46:47], v[46:47], v[88:89]
	s_waitcnt lgkmcnt(14)
	v_pk_fma_f32 v[50:51], v[66:67], v[62:63], v[50:51] op_sel_hi:[0,1,1]
	v_pk_fma_f32 v[46:47], v[66:67], v[58:59], v[46:47] op_sel_hi:[0,1,1]
	s_waitcnt lgkmcnt(13)
	v_pk_fma_f32 v[84:85], v[0:1], v[54:55], v[50:51] op_sel_hi:[0,1,1]
	v_pk_mul_f32 v[50:51], v[52:53], v[86:87]
	v_pk_fma_f32 v[88:89], v[0:1], v[42:43], v[46:47] op_sel_hi:[0,1,1]
	v_pk_mul_f32 v[42:43], v[48:49], v[90:91]
	v_pk_fma_f32 v[50:51], v[66:67], v[64:65], v[50:51] op_sel_hi:[0,1,1]
	v_pk_fma_f32 v[42:43], v[66:67], v[60:61], v[42:43] op_sel_hi:[0,1,1]
	s_add_i32 s46, s46, s3
	s_add_i32 s10, s10, 2
	s_addk_i32 s7, 0xc40
	v_pk_fma_f32 v[86:87], v[0:1], v[56:57], v[50:51] op_sel_hi:[0,1,1]
	v_pk_fma_f32 v[90:91], v[0:1], v[44:45], v[42:43] op_sel_hi:[0,1,1]
	s_waitcnt lgkmcnt(0)
	v_mov_b32_e32 v95, v96
	v_add_u32_e32 v96, s7, v100
	ds_read_b128 v[70:73], v96 offset:1568
	ds_read_b128 v[66:69], v96 offset:1584
	ds_read_b128 v[50:53], v96 offset:1824
	ds_read_b128 v[46:49], v96 offset:1840
	ds_read_b128 v[54:57], v96 offset:2080
	ds_read_b128 v[42:45], v96 offset:2096
	ds_read_b128 v[78:81], v96 offset:2336
	ds_read_b128 v[74:77], v96 offset:2352
	ds_read_b128 v[62:65], v96 offset:2592
	ds_read_b128 v[58:61], v96 offset:2608
	v_pk_fma_f32 v[34:35], v[84:85], v[34:35], 0 op_sel_hi:[1,1,0]
	v_pk_fma_f32 v[22:23], v[84:85], v[22:23], 0 op_sel_hi:[1,1,0]
	v_pk_fma_f32 v[34:35], v[86:87], v[36:37], v[34:35]
	v_pk_fma_f32 v[22:23], v[86:87], v[24:25], v[22:23]
	v_add_u32_e32 v103, s7, v102
	v_mov_b32_e32 v98, s7
	v_pk_fma_f32 v[24:25], v[88:89], v[38:39], v[34:35]
	v_pk_fma_f32 v[18:19], v[88:89], v[18:19], v[22:23]
	ds_read_b32 v0, v103 offset:2848
	ds_read_b64 v[98:99], v98 offset:3104
	v_pk_fma_f32 v[22:23], v[90:91], v[40:41], v[24:25]
	v_pk_fma_f32 v[20:21], v[90:91], v[20:21], v[18:19]
	v_add_f32_e32 v18, v22, v23
	v_add_f32_e32 v19, v20, v21
	s_nop 0
	v_add_f32_dpp v18, v18, v18 quad_perm:[1,0,3,2] row_mask:0xf bank_mask:0xf bound_ctrl:1
	v_add_f32_dpp v19, v19, v19 quad_perm:[1,0,3,2] row_mask:0xf bank_mask:0xf bound_ctrl:1
	s_nop 0
	v_add_f32_dpp v18, v18, v18 quad_perm:[2,3,0,1] row_mask:0xf bank_mask:0xf bound_ctrl:1
	v_add_f32_dpp v19, v19, v19 quad_perm:[2,3,0,1] row_mask:0xf bank_mask:0xf bound_ctrl:1
	s_nop 0
	v_add_f32_dpp v18, v18, v18 row_half_mirror row_mask:0xf bank_mask:0xf bound_ctrl:1
	v_mov_b32_e32 v22, v97
	v_mov_b32_e32 v23, v18
	v_pk_mul_f32 v[22:23], v[22:23], v[94:95]
	v_add_f32_dpp v19, v19, v19 row_half_mirror row_mask:0xf bank_mask:0xf bound_ctrl:1
	v_add_f32_e32 v19, v23, v19
	v_add_f32_e32 v19, v22, v19
	s_ashr_i32 s47, s46, 31
	v_bfe_u32 v20, v19, 16, 1
	s_lshl_b64 s[20:21], s[46:47], 9
	v_add3_u32 v19, v19, v20, s28
	v_lshl_add_u64 v[20:21], v[92:93], 0, s[20:21]
	global_store_short_d16_hi v[20:21], v19, off
	v_pk_mul_f32 v[2:3], v[84:85], v[2:3]
	s_nop 0
	v_pk_fma_f32 v[2:3], v[18:19], v[26:27], v[2:3] op_sel_hi:[0,1,1]
	v_pk_fma_f32 v[84:85], v[94:95], v[10:11], v[2:3] op_sel_hi:[0,1,1]
	v_pk_mul_f32 v[2:3], v[86:87], v[4:5]
	s_waitcnt lgkmcnt(5)
	v_pk_fma_f32 v[78:79], v[84:85], v[78:79], 0 op_sel_hi:[1,1,0]
	v_pk_fma_f32 v[2:3], v[18:19], v[28:29], v[2:3] op_sel_hi:[0,1,1]
	v_pk_fma_f32 v[86:87], v[94:95], v[12:13], v[2:3] op_sel_hi:[0,1,1]
	v_pk_mul_f32 v[2:3], v[88:89], v[6:7]
	v_pk_fma_f32 v[70:71], v[84:85], v[70:71], 0 op_sel_hi:[1,1,0]
	v_pk_fma_f32 v[2:3], v[18:19], v[30:31], v[2:3] op_sel_hi:[0,1,1]
	v_pk_fma_f32 v[88:89], v[94:95], v[14:15], v[2:3] op_sel_hi:[0,1,1]
	v_pk_mul_f32 v[2:3], v[90:91], v[8:9]
	v_pk_fma_f32 v[78:79], v[86:87], v[80:81], v[78:79]
	v_pk_fma_f32 v[2:3], v[18:19], v[32:33], v[2:3] op_sel_hi:[0,1,1]
	v_pk_fma_f32 v[90:91], v[94:95], v[16:17], v[2:3] op_sel_hi:[0,1,1]
	ds_read_b128 v[22:25], v96 offset:3136
	ds_read_b128 v[18:21], v96 offset:3152
	ds_read_b128 v[2:5], v96 offset:3392
	ds_read_b128 v[6:9], v96 offset:3408
	ds_read_b128 v[10:13], v96 offset:3648
	ds_read_b128 v[14:17], v96 offset:3664
	ds_read_b128 v[34:37], v96 offset:3904
	ds_read_b128 v[38:41], v96 offset:3920
	ds_read_b128 v[26:29], v96 offset:4160
	ds_read_b128 v[30:33], v96 offset:4176
	v_pk_fma_f32 v[70:71], v[86:87], v[72:73], v[70:71]
	s_waitcnt lgkmcnt(14)
	v_pk_fma_f32 v[72:73], v[88:89], v[74:75], v[78:79]
	v_pk_fma_f32 v[66:67], v[88:89], v[66:67], v[70:71]
	v_mov_b32_e32 v95, s7
	ds_read_b32 v94, v103 offset:4416
	ds_read_b64 v[96:97], v95 offset:4672
	v_pk_fma_f32 v[70:71], v[90:91], v[76:77], v[72:73]
	v_pk_fma_f32 v[68:69], v[90:91], v[68:69], v[66:67]
	v_add_f32_e32 v66, v70, v71
	v_add_f32_e32 v67, v68, v69
	s_nop 0
	v_add_f32_dpp v66, v66, v66 quad_perm:[1,0,3,2] row_mask:0xf bank_mask:0xf bound_ctrl:1
	v_add_f32_dpp v67, v67, v67 quad_perm:[1,0,3,2] row_mask:0xf bank_mask:0xf bound_ctrl:1
	s_nop 0
	v_add_f32_dpp v66, v66, v66 quad_perm:[2,3,0,1] row_mask:0xf bank_mask:0xf bound_ctrl:1
	v_add_f32_dpp v68, v67, v67 quad_perm:[2,3,0,1] row_mask:0xf bank_mask:0xf bound_ctrl:1
	s_nop 0
	v_add_f32_dpp v66, v66, v66 row_half_mirror row_mask:0xf bank_mask:0xf bound_ctrl:1
	s_waitcnt lgkmcnt(13)
	v_mov_b32_e32 v67, v0
	s_waitcnt lgkmcnt(12)
	v_pk_mul_f32 v[70:71], v[98:99], v[66:67]
	v_add_f32_dpp v67, v68, v68 row_half_mirror row_mask:0xf bank_mask:0xf bound_ctrl:1
	v_add_f32_e32 v67, v70, v67
	s_add_i32 s20, s2, s46
	v_add_f32_e32 v67, v71, v67
	s_ashr_i32 s21, s20, 31
	v_bfe_u32 v68, v67, 16, 1
	s_lshl_b64 s[20:21], s[20:21], 9
	v_add3_u32 v67, v67, v68, s28
	v_lshl_add_u64 v[68:69], v[92:93], 0, s[20:21]
	global_store_short_d16_hi v[68:69], v67, off
	v_pk_mul_f32 v[50:51], v[50:51], v[84:85]
	v_pk_mul_f32 v[46:47], v[46:47], v[88:89]
	s_waitcnt lgkmcnt(14)
	v_pk_fma_f32 v[50:51], v[66:67], v[62:63], v[50:51] op_sel_hi:[0,1,1]
	v_pk_fma_f32 v[46:47], v[66:67], v[58:59], v[46:47] op_sel_hi:[0,1,1]
	s_waitcnt lgkmcnt(13)
	v_pk_fma_f32 v[84:85], v[0:1], v[54:55], v[50:51] op_sel_hi:[0,1,1]
	v_pk_mul_f32 v[50:51], v[52:53], v[86:87]
	v_pk_fma_f32 v[88:89], v[0:1], v[42:43], v[46:47] op_sel_hi:[0,1,1]
	v_pk_mul_f32 v[42:43], v[48:49], v[90:91]
	v_pk_fma_f32 v[50:51], v[66:67], v[64:65], v[50:51] op_sel_hi:[0,1,1]
	v_pk_fma_f32 v[42:43], v[66:67], v[60:61], v[42:43] op_sel_hi:[0,1,1]
	s_add_i32 s46, s46, s3
	s_add_i32 s10, s10, 2
	s_addk_i32 s7, 0xc40
	v_pk_fma_f32 v[86:87], v[0:1], v[56:57], v[50:51] op_sel_hi:[0,1,1]
	s_cmp_gt_u32 s10, 13
	v_pk_fma_f32 v[90:91], v[0:1], v[44:45], v[42:43] op_sel_hi:[0,1,1]
	s_cbranch_scc0 .LBB0_859

.LBB0_869:
	s_waitcnt lgkmcnt(0)
	v_mov_b32_e32 v95, v96
	v_add_u32_e32 v96, s6, v100
	ds_read_b128 v[70:73], v96 offset:26656
	ds_read_b128 v[66:69], v96 offset:26672
	ds_read_b128 v[50:53], v96 offset:26912
	ds_read_b128 v[46:49], v96 offset:26928
	ds_read_b128 v[54:57], v96 offset:27168
	ds_read_b128 v[42:45], v96 offset:27184
	ds_read_b128 v[78:81], v96 offset:27424
	ds_read_b128 v[74:77], v96 offset:27440
	ds_read_b128 v[62:65], v96 offset:27680
	ds_read_b128 v[58:61], v96 offset:27696
	v_pk_fma_f32 v[34:35], v[84:85], v[34:35], 0 op_sel_hi:[1,1,0]
	v_pk_fma_f32 v[22:23], v[84:85], v[22:23], 0 op_sel_hi:[1,1,0]
	v_pk_fma_f32 v[34:35], v[86:87], v[36:37], v[34:35]
	v_pk_fma_f32 v[22:23], v[86:87], v[24:25], v[22:23]
	v_add_u32_e32 v103, s6, v102
	v_mov_b32_e32 v98, s6
	v_pk_fma_f32 v[24:25], v[88:89], v[38:39], v[34:35]
	v_pk_fma_f32 v[18:19], v[88:89], v[18:19], v[22:23]
	ds_read_b32 v0, v103 offset:27936
	ds_read_b64 v[98:99], v98 offset:28192
	v_pk_fma_f32 v[22:23], v[90:91], v[40:41], v[24:25]
	v_pk_fma_f32 v[20:21], v[90:91], v[20:21], v[18:19]
	v_add_f32_e32 v18, v22, v23
	v_add_f32_e32 v19, v20, v21
	s_nop 0
	v_add_f32_dpp v18, v18, v18 quad_perm:[1,0,3,2] row_mask:0xf bank_mask:0xf bound_ctrl:1
	v_add_f32_dpp v19, v19, v19 quad_perm:[1,0,3,2] row_mask:0xf bank_mask:0xf bound_ctrl:1
	s_nop 0
	v_add_f32_dpp v18, v18, v18 quad_perm:[2,3,0,1] row_mask:0xf bank_mask:0xf bound_ctrl:1
	v_add_f32_dpp v19, v19, v19 quad_perm:[2,3,0,1] row_mask:0xf bank_mask:0xf bound_ctrl:1
	s_nop 0
	v_add_f32_dpp v18, v18, v18 row_half_mirror row_mask:0xf bank_mask:0xf bound_ctrl:1
	v_mov_b32_e32 v22, v97
	v_mov_b32_e32 v23, v18
	v_pk_mul_f32 v[22:23], v[22:23], v[94:95]
	v_add_f32_dpp v19, v19, v19 row_half_mirror row_mask:0xf bank_mask:0xf bound_ctrl:1
	v_add_f32_e32 v19, v23, v19
	v_add_f32_e32 v19, v22, v19
	s_ashr_i32 s19, s18, 31
	v_bfe_u32 v20, v19, 16, 1
	s_lshl_b64 s[10:11], s[18:19], 9
	v_add3_u32 v19, v19, v20, s28
	v_lshl_add_u64 v[20:21], v[92:93], 0, s[10:11]
	global_store_short_d16_hi v[20:21], v19, off
	v_pk_mul_f32 v[2:3], v[84:85], v[2:3]
	s_nop 0
	v_pk_fma_f32 v[2:3], v[18:19], v[26:27], v[2:3] op_sel_hi:[0,1,1]
	v_pk_fma_f32 v[84:85], v[94:95], v[10:11], v[2:3] op_sel_hi:[0,1,1]
	v_pk_mul_f32 v[2:3], v[86:87], v[4:5]
	s_waitcnt lgkmcnt(5)
	v_pk_fma_f32 v[78:79], v[84:85], v[78:79], 0 op_sel_hi:[1,1,0]
	v_pk_fma_f32 v[2:3], v[18:19], v[28:29], v[2:3] op_sel_hi:[0,1,1]
	v_pk_fma_f32 v[86:87], v[94:95], v[12:13], v[2:3] op_sel_hi:[0,1,1]
	v_pk_mul_f32 v[2:3], v[88:89], v[6:7]
	v_pk_fma_f32 v[70:71], v[84:85], v[70:71], 0 op_sel_hi:[1,1,0]
	v_pk_fma_f32 v[2:3], v[18:19], v[30:31], v[2:3] op_sel_hi:[0,1,1]
	v_pk_fma_f32 v[88:89], v[94:95], v[14:15], v[2:3] op_sel_hi:[0,1,1]
	v_pk_mul_f32 v[2:3], v[90:91], v[8:9]
	v_pk_fma_f32 v[78:79], v[86:87], v[80:81], v[78:79]
	v_pk_fma_f32 v[2:3], v[18:19], v[32:33], v[2:3] op_sel_hi:[0,1,1]
	v_pk_fma_f32 v[90:91], v[94:95], v[16:17], v[2:3] op_sel_hi:[0,1,1]
	ds_read_b128 v[22:25], v96 offset:28224
	ds_read_b128 v[18:21], v96 offset:28240
	ds_read_b128 v[2:5], v96 offset:28480
	ds_read_b128 v[6:9], v96 offset:28496
	ds_read_b128 v[10:13], v96 offset:28736
	ds_read_b128 v[14:17], v96 offset:28752
	ds_read_b128 v[34:37], v96 offset:28992
	ds_read_b128 v[38:41], v96 offset:29008
	ds_read_b128 v[26:29], v96 offset:29248
	ds_read_b128 v[30:33], v96 offset:29264
	v_pk_fma_f32 v[70:71], v[86:87], v[72:73], v[70:71]
	s_waitcnt lgkmcnt(14)
	v_pk_fma_f32 v[72:73], v[88:89], v[74:75], v[78:79]
	v_pk_fma_f32 v[66:67], v[88:89], v[66:67], v[70:71]
	v_mov_b32_e32 v95, s6
	ds_read_b32 v94, v103 offset:29504
	ds_read_b64 v[96:97], v95 offset:29760
	v_pk_fma_f32 v[70:71], v[90:91], v[76:77], v[72:73]
	v_pk_fma_f32 v[68:69], v[90:91], v[68:69], v[66:67]
	v_add_f32_e32 v66, v70, v71
	v_add_f32_e32 v67, v68, v69
	s_nop 0
	v_add_f32_dpp v66, v66, v66 quad_perm:[1,0,3,2] row_mask:0xf bank_mask:0xf bound_ctrl:1
	v_add_f32_dpp v67, v67, v67 quad_perm:[1,0,3,2] row_mask:0xf bank_mask:0xf bound_ctrl:1
	s_nop 0
	v_add_f32_dpp v66, v66, v66 quad_perm:[2,3,0,1] row_mask:0xf bank_mask:0xf bound_ctrl:1
	v_add_f32_dpp v68, v67, v67 quad_perm:[2,3,0,1] row_mask:0xf bank_mask:0xf bound_ctrl:1
	s_nop 0
	v_add_f32_dpp v66, v66, v66 row_half_mirror row_mask:0xf bank_mask:0xf bound_ctrl:1
	s_waitcnt lgkmcnt(13)
	v_mov_b32_e32 v67, v0
	s_waitcnt lgkmcnt(12)
	v_pk_mul_f32 v[70:71], v[98:99], v[66:67]
	v_add_f32_dpp v67, v68, v68 row_half_mirror row_mask:0xf bank_mask:0xf bound_ctrl:1
	v_add_f32_e32 v67, v70, v67
	s_add_i32 s10, s2, s18
	v_add_f32_e32 v67, v71, v67
	s_ashr_i32 s11, s10, 31
	v_bfe_u32 v68, v67, 16, 1
	s_lshl_b64 s[10:11], s[10:11], 9
	v_add3_u32 v67, v67, v68, s28
	v_lshl_add_u64 v[68:69], v[92:93], 0, s[10:11]
	global_store_short_d16_hi v[68:69], v67, off
	v_pk_mul_f32 v[50:51], v[50:51], v[84:85]
	v_pk_mul_f32 v[46:47], v[46:47], v[88:89]
	s_waitcnt lgkmcnt(14)
	v_pk_fma_f32 v[50:51], v[66:67], v[62:63], v[50:51] op_sel_hi:[0,1,1]
	v_pk_fma_f32 v[46:47], v[66:67], v[58:59], v[46:47] op_sel_hi:[0,1,1]
	s_waitcnt lgkmcnt(13)
	v_pk_fma_f32 v[84:85], v[0:1], v[54:55], v[50:51] op_sel_hi:[0,1,1]
	v_pk_mul_f32 v[50:51], v[52:53], v[86:87]
	v_pk_fma_f32 v[88:89], v[0:1], v[42:43], v[46:47] op_sel_hi:[0,1,1]
	v_pk_mul_f32 v[42:43], v[48:49], v[90:91]
	v_pk_fma_f32 v[50:51], v[66:67], v[64:65], v[50:51] op_sel_hi:[0,1,1]
	v_pk_fma_f32 v[42:43], v[66:67], v[60:61], v[42:43] op_sel_hi:[0,1,1]
	s_add_i32 s18, s18, s3
	s_add_i32 s7, s7, 2
	s_addk_i32 s6, 0xc40
	v_pk_fma_f32 v[86:87], v[0:1], v[56:57], v[50:51] op_sel_hi:[0,1,1]
	v_pk_fma_f32 v[90:91], v[0:1], v[44:45], v[42:43] op_sel_hi:[0,1,1]
	s_waitcnt lgkmcnt(0)
	v_mov_b32_e32 v95, v96
	v_add_u32_e32 v96, s6, v100
	ds_read_b128 v[70:73], v96 offset:26656
	ds_read_b128 v[66:69], v96 offset:26672
	ds_read_b128 v[50:53], v96 offset:26912
	ds_read_b128 v[46:49], v96 offset:26928
	ds_read_b128 v[54:57], v96 offset:27168
	ds_read_b128 v[42:45], v96 offset:27184
	ds_read_b128 v[78:81], v96 offset:27424
	ds_read_b128 v[74:77], v96 offset:27440
	ds_read_b128 v[62:65], v96 offset:27680
	ds_read_b128 v[58:61], v96 offset:27696
	v_pk_fma_f32 v[34:35], v[84:85], v[34:35], 0 op_sel_hi:[1,1,0]
	v_pk_fma_f32 v[22:23], v[84:85], v[22:23], 0 op_sel_hi:[1,1,0]
	v_pk_fma_f32 v[34:35], v[86:87], v[36:37], v[34:35]
	v_pk_fma_f32 v[22:23], v[86:87], v[24:25], v[22:23]
	v_add_u32_e32 v103, s6, v102
	v_mov_b32_e32 v98, s6
	v_pk_fma_f32 v[24:25], v[88:89], v[38:39], v[34:35]
	v_pk_fma_f32 v[18:19], v[88:89], v[18:19], v[22:23]
	ds_read_b32 v0, v103 offset:27936
	ds_read_b64 v[98:99], v98 offset:28192
	v_pk_fma_f32 v[22:23], v[90:91], v[40:41], v[24:25]
	v_pk_fma_f32 v[20:21], v[90:91], v[20:21], v[18:19]
	v_add_f32_e32 v18, v22, v23
	v_add_f32_e32 v19, v20, v21
	s_nop 0
	v_add_f32_dpp v18, v18, v18 quad_perm:[1,0,3,2] row_mask:0xf bank_mask:0xf bound_ctrl:1
	v_add_f32_dpp v19, v19, v19 quad_perm:[1,0,3,2] row_mask:0xf bank_mask:0xf bound_ctrl:1
	s_nop 0
	v_add_f32_dpp v18, v18, v18 quad_perm:[2,3,0,1] row_mask:0xf bank_mask:0xf bound_ctrl:1
	v_add_f32_dpp v19, v19, v19 quad_perm:[2,3,0,1] row_mask:0xf bank_mask:0xf bound_ctrl:1
	s_nop 0
	v_add_f32_dpp v18, v18, v18 row_half_mirror row_mask:0xf bank_mask:0xf bound_ctrl:1
	v_mov_b32_e32 v22, v97
	v_mov_b32_e32 v23, v18
	v_pk_mul_f32 v[22:23], v[22:23], v[94:95]
	v_add_f32_dpp v19, v19, v19 row_half_mirror row_mask:0xf bank_mask:0xf bound_ctrl:1
	v_add_f32_e32 v19, v23, v19
	v_add_f32_e32 v19, v22, v19
	s_ashr_i32 s19, s18, 31
	v_bfe_u32 v20, v19, 16, 1
	s_lshl_b64 s[10:11], s[18:19], 9
	v_add3_u32 v19, v19, v20, s28
	v_lshl_add_u64 v[20:21], v[92:93], 0, s[10:11]
	global_store_short_d16_hi v[20:21], v19, off
	v_pk_mul_f32 v[2:3], v[84:85], v[2:3]
	s_nop 0
	v_pk_fma_f32 v[2:3], v[18:19], v[26:27], v[2:3] op_sel_hi:[0,1,1]
	v_pk_fma_f32 v[84:85], v[94:95], v[10:11], v[2:3] op_sel_hi:[0,1,1]
	v_pk_mul_f32 v[2:3], v[86:87], v[4:5]
	s_waitcnt lgkmcnt(5)
	v_pk_fma_f32 v[78:79], v[84:85], v[78:79], 0 op_sel_hi:[1,1,0]
	v_pk_fma_f32 v[2:3], v[18:19], v[28:29], v[2:3] op_sel_hi:[0,1,1]
	v_pk_fma_f32 v[86:87], v[94:95], v[12:13], v[2:3] op_sel_hi:[0,1,1]
	v_pk_mul_f32 v[2:3], v[88:89], v[6:7]
	v_pk_fma_f32 v[70:71], v[84:85], v[70:71], 0 op_sel_hi:[1,1,0]
	v_pk_fma_f32 v[2:3], v[18:19], v[30:31], v[2:3] op_sel_hi:[0,1,1]
	v_pk_fma_f32 v[88:89], v[94:95], v[14:15], v[2:3] op_sel_hi:[0,1,1]
	v_pk_mul_f32 v[2:3], v[90:91], v[8:9]
	v_pk_fma_f32 v[78:79], v[86:87], v[80:81], v[78:79]
	v_pk_fma_f32 v[2:3], v[18:19], v[32:33], v[2:3] op_sel_hi:[0,1,1]
	v_pk_fma_f32 v[90:91], v[94:95], v[16:17], v[2:3] op_sel_hi:[0,1,1]
	ds_read_b128 v[22:25], v96 offset:28224
	ds_read_b128 v[18:21], v96 offset:28240
	ds_read_b128 v[2:5], v96 offset:28480
	ds_read_b128 v[6:9], v96 offset:28496
	ds_read_b128 v[10:13], v96 offset:28736
	ds_read_b128 v[14:17], v96 offset:28752
	ds_read_b128 v[34:37], v96 offset:28992
	ds_read_b128 v[38:41], v96 offset:29008
	ds_read_b128 v[26:29], v96 offset:29248
	ds_read_b128 v[30:33], v96 offset:29264
	v_pk_fma_f32 v[70:71], v[86:87], v[72:73], v[70:71]
	s_waitcnt lgkmcnt(14)
	v_pk_fma_f32 v[72:73], v[88:89], v[74:75], v[78:79]
	v_pk_fma_f32 v[66:67], v[88:89], v[66:67], v[70:71]
	v_mov_b32_e32 v95, s6
	ds_read_b32 v94, v103 offset:29504
	ds_read_b64 v[96:97], v95 offset:29760
	v_pk_fma_f32 v[70:71], v[90:91], v[76:77], v[72:73]
	v_pk_fma_f32 v[68:69], v[90:91], v[68:69], v[66:67]
	v_add_f32_e32 v66, v70, v71
	v_add_f32_e32 v67, v68, v69
	s_nop 0
	v_add_f32_dpp v66, v66, v66 quad_perm:[1,0,3,2] row_mask:0xf bank_mask:0xf bound_ctrl:1
	v_add_f32_dpp v67, v67, v67 quad_perm:[1,0,3,2] row_mask:0xf bank_mask:0xf bound_ctrl:1
	s_nop 0
	v_add_f32_dpp v66, v66, v66 quad_perm:[2,3,0,1] row_mask:0xf bank_mask:0xf bound_ctrl:1
	v_add_f32_dpp v68, v67, v67 quad_perm:[2,3,0,1] row_mask:0xf bank_mask:0xf bound_ctrl:1
	s_nop 0
	v_add_f32_dpp v66, v66, v66 row_half_mirror row_mask:0xf bank_mask:0xf bound_ctrl:1
	s_waitcnt lgkmcnt(13)
	v_mov_b32_e32 v67, v0
	s_waitcnt lgkmcnt(12)
	v_pk_mul_f32 v[70:71], v[98:99], v[66:67]
	v_add_f32_dpp v67, v68, v68 row_half_mirror row_mask:0xf bank_mask:0xf bound_ctrl:1
	v_add_f32_e32 v67, v70, v67
	s_add_i32 s10, s2, s18
	v_add_f32_e32 v67, v71, v67
	s_ashr_i32 s11, s10, 31
	v_bfe_u32 v68, v67, 16, 1
	s_lshl_b64 s[10:11], s[10:11], 9
	v_add3_u32 v67, v67, v68, s28
	v_lshl_add_u64 v[68:69], v[92:93], 0, s[10:11]
	global_store_short_d16_hi v[68:69], v67, off
	v_pk_mul_f32 v[50:51], v[50:51], v[84:85]
	v_pk_mul_f32 v[46:47], v[46:47], v[88:89]
	s_waitcnt lgkmcnt(14)
	v_pk_fma_f32 v[50:51], v[66:67], v[62:63], v[50:51] op_sel_hi:[0,1,1]
	v_pk_fma_f32 v[46:47], v[66:67], v[58:59], v[46:47] op_sel_hi:[0,1,1]
	s_waitcnt lgkmcnt(13)
	v_pk_fma_f32 v[84:85], v[0:1], v[54:55], v[50:51] op_sel_hi:[0,1,1]
	v_pk_mul_f32 v[50:51], v[52:53], v[86:87]
	v_pk_fma_f32 v[88:89], v[0:1], v[42:43], v[46:47] op_sel_hi:[0,1,1]
	v_pk_mul_f32 v[42:43], v[48:49], v[90:91]
	v_pk_fma_f32 v[50:51], v[66:67], v[64:65], v[50:51] op_sel_hi:[0,1,1]
	v_pk_fma_f32 v[42:43], v[66:67], v[60:61], v[42:43] op_sel_hi:[0,1,1]
	s_add_i32 s18, s18, s3
	s_add_i32 s7, s7, 2
	s_addk_i32 s6, 0xc40
	v_pk_fma_f32 v[86:87], v[0:1], v[56:57], v[50:51] op_sel_hi:[0,1,1]
	s_cmp_gt_u32 s7, 13
	v_pk_fma_f32 v[90:91], v[0:1], v[44:45], v[42:43] op_sel_hi:[0,1,1]
	s_cbranch_scc0 .LBB0_869
	s_branch .LBB0_852

.LBB0_906:
	s_waitcnt lgkmcnt(5)
	v_pk_fma_f32 v[100:101], v[74:75], v[2:3], 0 op_sel_hi:[1,1,0]
	s_waitcnt lgkmcnt(0)
	v_mov_b32_e32 v37, v34
	v_add_u32_e32 v34, s7, v94
	v_pk_fma_f32 v[30:31], v[74:75], v[30:31], 0 op_sel_hi:[1,1,0]
	v_pk_fma_f32 v[100:101], v[78:79], v[4:5], v[100:101]
	ds_read_b128 v[66:69], v34 offset:800
	ds_read_b128 v[62:65], v34 offset:816
	ds_read_b128 v[58:61], v34 offset:832
	ds_read_b128 v[54:57], v34 offset:848
	ds_read_b128 v[50:53], v34 offset:1056
	ds_read_b128 v[46:49], v34 offset:1072
	ds_read_b128 v[42:45], v34 offset:1088
	ds_read_b128 v[38:41], v34 offset:1104
	v_pk_fma_f32 v[30:31], v[78:79], v[32:33], v[30:31]
	v_pk_fma_f32 v[32:33], v[80:81], v[6:7], v[100:101]
	v_pk_fma_f32 v[26:27], v[80:81], v[26:27], v[30:31]
	v_pk_fma_f32 v[30:31], v[82:83], v[8:9], v[32:33]
	v_pk_fma_f32 v[26:27], v[82:83], v[28:29], v[26:27]
	s_waitcnt lgkmcnt(9)
	v_pk_fma_f32 v[28:29], v[84:85], v[14:15], v[30:31]
	v_pk_fma_f32 v[22:23], v[84:85], v[22:23], v[26:27]
	v_pk_fma_f32 v[26:27], v[86:87], v[16:17], v[28:29]
	v_pk_fma_f32 v[22:23], v[86:87], v[24:25], v[22:23]
	s_waitcnt lgkmcnt(8)
	v_pk_fma_f32 v[24:25], v[88:89], v[10:11], v[26:27]
	v_add_u32_e32 v98, s7, v97
	v_mov_b32_e32 v70, s7
	v_pk_fma_f32 v[18:19], v[88:89], v[18:19], v[22:23]
	v_pk_fma_f32 v[22:23], v[90:91], v[12:13], v[24:25]
	ds_read_b32 v0, v98
	ds_read_b96 v[70:72], v70 offset:1568
	v_pk_fma_f32 v[18:19], v[90:91], v[20:21], v[18:19]
	v_add_f32_e32 v20, v22, v23
	v_add_f32_e32 v18, v18, v19
	s_nop 0
	v_add_f32_dpp v20, v20, v20 quad_perm:[1,0,3,2] row_mask:0xf bank_mask:0xf bound_ctrl:1
	v_add_f32_dpp v19, v18, v18 quad_perm:[1,0,3,2] row_mask:0xf bank_mask:0xf bound_ctrl:1
	s_nop 0
	v_add_f32_dpp v20, v20, v20 quad_perm:[2,3,0,1] row_mask:0xf bank_mask:0xf bound_ctrl:1
	v_fma_f32 v18, -v37, v20, v73
	v_mul_f32_e32 v18, v35, v18
	v_add_f32_dpp v19, v19, v19 quad_perm:[2,3,0,1] row_mask:0xf bank_mask:0xf bound_ctrl:1
	v_mul_f32_e32 v20, v37, v19
	v_pk_fma_f32 v[20:21], v[36:37], v[18:19], v[20:21] op_sel_hi:[1,1,0]
	s_ashr_i32 s19, s18, 31
	v_bfe_u32 v19, v20, 16, 1
	s_lshl_b64 s[20:21], s[18:19], 9
	v_add3_u32 v19, v20, v19, s28
	v_lshl_add_u64 v[20:21], v[92:93], 0, s[20:21]
	global_store_short_d16_hi v[20:21], v19, off
	v_pk_mul_f32 v[20:21], v[74:75], v[36:37] op_sel:[0,1]
	s_nop 0
	v_pk_fma_f32 v[74:75], v[2:3], v[18:19], v[20:21] op_sel_hi:[1,0,1]
	v_pk_mul_f32 v[2:3], v[78:79], v[36:37] op_sel:[0,1]
	s_waitcnt lgkmcnt(9)
	v_pk_fma_f32 v[66:67], v[74:75], v[66:67], 0 op_sel_hi:[1,1,0]
	v_pk_fma_f32 v[78:79], v[4:5], v[18:19], v[2:3] op_sel_hi:[1,0,1]
	v_pk_mul_f32 v[2:3], v[80:81], v[36:37] op_sel:[0,1]
	v_pk_fma_f32 v[66:67], v[78:79], v[68:69], v[66:67]
	v_pk_fma_f32 v[80:81], v[6:7], v[18:19], v[2:3] op_sel_hi:[1,0,1]
	v_pk_mul_f32 v[2:3], v[82:83], v[36:37] op_sel:[0,1]
	s_waitcnt lgkmcnt(8)
	v_pk_fma_f32 v[62:63], v[80:81], v[62:63], v[66:67]
	v_pk_fma_f32 v[82:83], v[8:9], v[18:19], v[2:3] op_sel_hi:[1,0,1]
	v_pk_mul_f32 v[2:3], v[84:85], v[36:37] op_sel:[0,1]
	v_pk_fma_f32 v[62:63], v[82:83], v[64:65], v[62:63]
	v_pk_fma_f32 v[84:85], v[14:15], v[18:19], v[2:3] op_sel_hi:[1,0,1]
	v_pk_mul_f32 v[2:3], v[86:87], v[36:37] op_sel:[0,1]
	s_waitcnt lgkmcnt(7)
	v_pk_fma_f32 v[58:59], v[84:85], v[58:59], v[62:63]
	v_pk_fma_f32 v[86:87], v[16:17], v[18:19], v[2:3] op_sel_hi:[1,0,1]
	v_pk_mul_f32 v[2:3], v[88:89], v[36:37] op_sel:[0,1]
	v_pk_fma_f32 v[58:59], v[86:87], v[60:61], v[58:59]
	v_pk_fma_f32 v[88:89], v[10:11], v[18:19], v[2:3] op_sel_hi:[1,0,1]
	v_pk_mul_f32 v[2:3], v[90:91], v[36:37] op_sel:[0,1]
	s_waitcnt lgkmcnt(6)
	v_pk_fma_f32 v[54:55], v[88:89], v[54:55], v[58:59]
	v_pk_fma_f32 v[90:91], v[12:13], v[18:19], v[2:3] op_sel_hi:[1,0,1]
	ds_read_b128 v[30:33], v34 offset:1600
	ds_read_b128 v[26:29], v34 offset:1616
	ds_read_b128 v[22:25], v34 offset:1632
	ds_read_b128 v[18:21], v34 offset:1648
	ds_read_b128 v[2:5], v34 offset:1856
	ds_read_b128 v[6:9], v34 offset:1872
	ds_read_b128 v[14:17], v34 offset:1888
	ds_read_b128 v[10:13], v34 offset:1904
	v_mov_b32_e32 v34, s7
	ds_read_b32 v73, v98 offset:800
	ds_read_b96 v[34:36], v34 offset:2368
	s_waitcnt lgkmcnt(14)
	v_pk_fma_f32 v[98:99], v[74:75], v[50:51], 0 op_sel_hi:[1,1,0]
	v_pk_fma_f32 v[54:55], v[90:91], v[56:57], v[54:55]
	v_pk_fma_f32 v[98:99], v[78:79], v[52:53], v[98:99]
	s_nop 0
	v_pk_fma_f32 v[68:69], v[80:81], v[46:47], v[98:99]
	s_nop 0
	v_pk_fma_f32 v[66:67], v[82:83], v[48:49], v[68:69]
	s_waitcnt lgkmcnt(13)
	v_pk_fma_f32 v[64:65], v[84:85], v[42:43], v[66:67]
	s_nop 0
	v_pk_fma_f32 v[62:63], v[86:87], v[44:45], v[64:65]
	s_waitcnt lgkmcnt(12)
	v_pk_fma_f32 v[60:61], v[88:89], v[38:39], v[62:63]
	s_nop 0
	v_pk_fma_f32 v[58:59], v[90:91], v[40:41], v[60:61]
	s_nop 0
	v_add_f32_e32 v37, v58, v59
	s_nop 1
	v_add_f32_dpp v37, v37, v37 quad_perm:[1,0,3,2] row_mask:0xf bank_mask:0xf bound_ctrl:1
	s_nop 1
	v_add_f32_dpp v56, v37, v37 quad_perm:[2,3,0,1] row_mask:0xf bank_mask:0xf bound_ctrl:1
	v_add_f32_e32 v37, v54, v55
	s_waitcnt lgkmcnt(10)
	v_fma_f32 v0, -v70, v56, v0
	v_mul_f32_e32 v0, v71, v0
	v_add_f32_dpp v37, v37, v37 quad_perm:[1,0,3,2] row_mask:0xf bank_mask:0xf bound_ctrl:1
	s_nop 1
	v_add_f32_dpp v54, v37, v37 quad_perm:[2,3,0,1] row_mask:0xf bank_mask:0xf bound_ctrl:1
	v_mov_b32_e32 v71, v72
	v_mov_b32_e32 v55, v0
	v_mul_f32_e32 v56, v72, v0
	s_add_i32 s20, s24, s18
	v_pk_fma_f32 v[54:55], v[70:71], v[54:55], v[56:57] op_sel_hi:[1,1,0]
	s_ashr_i32 s21, s20, 31
	v_bfe_u32 v37, v54, 16, 1
	s_lshl_b64 s[20:21], s[20:21], 9
	v_add3_u32 v37, v54, v37, s28
	v_lshl_add_u64 v[54:55], v[92:93], 0, s[20:21]
	global_store_short_d16_hi v[54:55], v37, off
	v_pk_mul_f32 v[54:55], v[70:71], v[74:75] op_sel_hi:[0,1]
	v_pk_fma_f32 v[74:75], v[50:51], v[0:1], v[54:55] op_sel_hi:[1,0,1]
	v_pk_mul_f32 v[50:51], v[70:71], v[78:79] op_sel_hi:[0,1]
	v_pk_fma_f32 v[78:79], v[52:53], v[0:1], v[50:51] op_sel_hi:[1,0,1]
	v_pk_mul_f32 v[50:51], v[70:71], v[80:81] op_sel_hi:[0,1]
	v_pk_fma_f32 v[80:81], v[46:47], v[0:1], v[50:51] op_sel_hi:[1,0,1]
	v_pk_mul_f32 v[46:47], v[70:71], v[82:83] op_sel_hi:[0,1]
	v_pk_fma_f32 v[82:83], v[48:49], v[0:1], v[46:47] op_sel_hi:[1,0,1]
	v_pk_mul_f32 v[46:47], v[70:71], v[84:85] op_sel_hi:[0,1]
	v_pk_fma_f32 v[84:85], v[42:43], v[0:1], v[46:47] op_sel_hi:[1,0,1]
	v_pk_mul_f32 v[42:43], v[70:71], v[86:87] op_sel_hi:[0,1]
	v_pk_fma_f32 v[86:87], v[44:45], v[0:1], v[42:43] op_sel_hi:[1,0,1]
	v_pk_mul_f32 v[42:43], v[70:71], v[88:89] op_sel_hi:[0,1]
	v_pk_fma_f32 v[88:89], v[38:39], v[0:1], v[42:43] op_sel_hi:[1,0,1]
	v_pk_mul_f32 v[38:39], v[70:71], v[90:91] op_sel_hi:[0,1]
	s_add_i32 s18, s18, s25
	s_add_i32 s10, s10, 2
	s_addk_i32 s7, 0x640
	v_pk_fma_f32 v[90:91], v[40:41], v[0:1], v[38:39] op_sel_hi:[1,0,1]
	s_waitcnt lgkmcnt(5)
	v_pk_fma_f32 v[100:101], v[74:75], v[2:3], 0 op_sel_hi:[1,1,0]
	s_waitcnt lgkmcnt(0)
	v_mov_b32_e32 v37, v34
	v_add_u32_e32 v34, s7, v94
	v_pk_fma_f32 v[30:31], v[74:75], v[30:31], 0 op_sel_hi:[1,1,0]
	v_pk_fma_f32 v[100:101], v[78:79], v[4:5], v[100:101]
	ds_read_b128 v[66:69], v34 offset:800
	ds_read_b128 v[62:65], v34 offset:816
	ds_read_b128 v[58:61], v34 offset:832
	ds_read_b128 v[54:57], v34 offset:848
	ds_read_b128 v[50:53], v34 offset:1056
	ds_read_b128 v[46:49], v34 offset:1072
	ds_read_b128 v[42:45], v34 offset:1088
	ds_read_b128 v[38:41], v34 offset:1104
	v_pk_fma_f32 v[30:31], v[78:79], v[32:33], v[30:31]
	v_pk_fma_f32 v[32:33], v[80:81], v[6:7], v[100:101]
	v_pk_fma_f32 v[26:27], v[80:81], v[26:27], v[30:31]
	v_pk_fma_f32 v[30:31], v[82:83], v[8:9], v[32:33]
	v_pk_fma_f32 v[26:27], v[82:83], v[28:29], v[26:27]
	s_waitcnt lgkmcnt(9)
	v_pk_fma_f32 v[28:29], v[84:85], v[14:15], v[30:31]
	v_pk_fma_f32 v[22:23], v[84:85], v[22:23], v[26:27]
	v_pk_fma_f32 v[26:27], v[86:87], v[16:17], v[28:29]
	v_pk_fma_f32 v[22:23], v[86:87], v[24:25], v[22:23]
	s_waitcnt lgkmcnt(8)
	v_pk_fma_f32 v[24:25], v[88:89], v[10:11], v[26:27]
	v_add_u32_e32 v98, s7, v97
	v_mov_b32_e32 v70, s7
	v_pk_fma_f32 v[18:19], v[88:89], v[18:19], v[22:23]
	v_pk_fma_f32 v[22:23], v[90:91], v[12:13], v[24:25]
	ds_read_b32 v0, v98
	ds_read_b96 v[70:72], v70 offset:1568
	v_pk_fma_f32 v[18:19], v[90:91], v[20:21], v[18:19]
	v_add_f32_e32 v20, v22, v23
	v_add_f32_e32 v18, v18, v19
	s_nop 0
	v_add_f32_dpp v20, v20, v20 quad_perm:[1,0,3,2] row_mask:0xf bank_mask:0xf bound_ctrl:1
	v_add_f32_dpp v19, v18, v18 quad_perm:[1,0,3,2] row_mask:0xf bank_mask:0xf bound_ctrl:1
	s_nop 0
	v_add_f32_dpp v20, v20, v20 quad_perm:[2,3,0,1] row_mask:0xf bank_mask:0xf bound_ctrl:1
	v_fma_f32 v18, -v37, v20, v73
	v_mul_f32_e32 v18, v35, v18
	v_add_f32_dpp v19, v19, v19 quad_perm:[2,3,0,1] row_mask:0xf bank_mask:0xf bound_ctrl:1
	v_mul_f32_e32 v20, v37, v19
	v_pk_fma_f32 v[20:21], v[36:37], v[18:19], v[20:21] op_sel_hi:[1,1,0]
	s_ashr_i32 s19, s18, 31
	v_bfe_u32 v19, v20, 16, 1
	s_lshl_b64 s[20:21], s[18:19], 9
	v_add3_u32 v19, v20, v19, s28
	v_lshl_add_u64 v[20:21], v[92:93], 0, s[20:21]
	global_store_short_d16_hi v[20:21], v19, off
	v_pk_mul_f32 v[20:21], v[74:75], v[36:37] op_sel:[0,1]
	s_nop 0
	v_pk_fma_f32 v[74:75], v[2:3], v[18:19], v[20:21] op_sel_hi:[1,0,1]
	v_pk_mul_f32 v[2:3], v[78:79], v[36:37] op_sel:[0,1]
	s_waitcnt lgkmcnt(9)
	v_pk_fma_f32 v[66:67], v[74:75], v[66:67], 0 op_sel_hi:[1,1,0]
	v_pk_fma_f32 v[78:79], v[4:5], v[18:19], v[2:3] op_sel_hi:[1,0,1]
	v_pk_mul_f32 v[2:3], v[80:81], v[36:37] op_sel:[0,1]
	v_pk_fma_f32 v[66:67], v[78:79], v[68:69], v[66:67]
	v_pk_fma_f32 v[80:81], v[6:7], v[18:19], v[2:3] op_sel_hi:[1,0,1]
	v_pk_mul_f32 v[2:3], v[82:83], v[36:37] op_sel:[0,1]
	s_waitcnt lgkmcnt(8)
	v_pk_fma_f32 v[62:63], v[80:81], v[62:63], v[66:67]
	v_pk_fma_f32 v[82:83], v[8:9], v[18:19], v[2:3] op_sel_hi:[1,0,1]
	v_pk_mul_f32 v[2:3], v[84:85], v[36:37] op_sel:[0,1]
	v_pk_fma_f32 v[62:63], v[82:83], v[64:65], v[62:63]
	v_pk_fma_f32 v[84:85], v[14:15], v[18:19], v[2:3] op_sel_hi:[1,0,1]
	v_pk_mul_f32 v[2:3], v[86:87], v[36:37] op_sel:[0,1]
	s_waitcnt lgkmcnt(7)
	v_pk_fma_f32 v[58:59], v[84:85], v[58:59], v[62:63]
	v_pk_fma_f32 v[86:87], v[16:17], v[18:19], v[2:3] op_sel_hi:[1,0,1]
	v_pk_mul_f32 v[2:3], v[88:89], v[36:37] op_sel:[0,1]
	v_pk_fma_f32 v[58:59], v[86:87], v[60:61], v[58:59]
	v_pk_fma_f32 v[88:89], v[10:11], v[18:19], v[2:3] op_sel_hi:[1,0,1]
	v_pk_mul_f32 v[2:3], v[90:91], v[36:37] op_sel:[0,1]
	s_waitcnt lgkmcnt(6)
	v_pk_fma_f32 v[54:55], v[88:89], v[54:55], v[58:59]
	v_pk_fma_f32 v[90:91], v[12:13], v[18:19], v[2:3] op_sel_hi:[1,0,1]
	ds_read_b128 v[30:33], v34 offset:1600
	ds_read_b128 v[26:29], v34 offset:1616
	ds_read_b128 v[22:25], v34 offset:1632
	ds_read_b128 v[18:21], v34 offset:1648
	ds_read_b128 v[2:5], v34 offset:1856
	ds_read_b128 v[6:9], v34 offset:1872
	ds_read_b128 v[14:17], v34 offset:1888
	ds_read_b128 v[10:13], v34 offset:1904
	v_mov_b32_e32 v34, s7
	ds_read_b32 v73, v98 offset:800
	ds_read_b96 v[34:36], v34 offset:2368
	s_waitcnt lgkmcnt(14)
	v_pk_fma_f32 v[98:99], v[74:75], v[50:51], 0 op_sel_hi:[1,1,0]
	v_pk_fma_f32 v[54:55], v[90:91], v[56:57], v[54:55]
	v_pk_fma_f32 v[98:99], v[78:79], v[52:53], v[98:99]
	s_nop 0
	v_pk_fma_f32 v[68:69], v[80:81], v[46:47], v[98:99]
	s_nop 0
	v_pk_fma_f32 v[66:67], v[82:83], v[48:49], v[68:69]
	s_waitcnt lgkmcnt(13)
	v_pk_fma_f32 v[64:65], v[84:85], v[42:43], v[66:67]
	s_nop 0
	v_pk_fma_f32 v[62:63], v[86:87], v[44:45], v[64:65]
	s_waitcnt lgkmcnt(12)
	v_pk_fma_f32 v[60:61], v[88:89], v[38:39], v[62:63]
	s_nop 0
	v_pk_fma_f32 v[58:59], v[90:91], v[40:41], v[60:61]
	s_nop 0
	v_add_f32_e32 v37, v58, v59
	s_nop 1
	v_add_f32_dpp v37, v37, v37 quad_perm:[1,0,3,2] row_mask:0xf bank_mask:0xf bound_ctrl:1
	s_nop 1
	v_add_f32_dpp v56, v37, v37 quad_perm:[2,3,0,1] row_mask:0xf bank_mask:0xf bound_ctrl:1
	v_add_f32_e32 v37, v54, v55
	s_waitcnt lgkmcnt(10)
	v_fma_f32 v0, -v70, v56, v0
	v_mul_f32_e32 v0, v71, v0
	v_add_f32_dpp v37, v37, v37 quad_perm:[1,0,3,2] row_mask:0xf bank_mask:0xf bound_ctrl:1
	s_nop 1
	v_add_f32_dpp v54, v37, v37 quad_perm:[2,3,0,1] row_mask:0xf bank_mask:0xf bound_ctrl:1
	v_mov_b32_e32 v71, v72
	v_mov_b32_e32 v55, v0
	v_mul_f32_e32 v56, v72, v0
	s_add_i32 s20, s24, s18
	v_pk_fma_f32 v[54:55], v[70:71], v[54:55], v[56:57] op_sel_hi:[1,1,0]
	s_ashr_i32 s21, s20, 31
	v_bfe_u32 v37, v54, 16, 1
	s_lshl_b64 s[20:21], s[20:21], 9
	v_add3_u32 v37, v54, v37, s28
	v_lshl_add_u64 v[54:55], v[92:93], 0, s[20:21]
	global_store_short_d16_hi v[54:55], v37, off
	v_pk_mul_f32 v[54:55], v[70:71], v[74:75] op_sel_hi:[0,1]
	v_pk_fma_f32 v[74:75], v[50:51], v[0:1], v[54:55] op_sel_hi:[1,0,1]
	v_pk_mul_f32 v[50:51], v[70:71], v[78:79] op_sel_hi:[0,1]
	v_pk_fma_f32 v[78:79], v[52:53], v[0:1], v[50:51] op_sel_hi:[1,0,1]
	v_pk_mul_f32 v[50:51], v[70:71], v[80:81] op_sel_hi:[0,1]
	v_pk_fma_f32 v[80:81], v[46:47], v[0:1], v[50:51] op_sel_hi:[1,0,1]
	v_pk_mul_f32 v[46:47], v[70:71], v[82:83] op_sel_hi:[0,1]
	v_pk_fma_f32 v[82:83], v[48:49], v[0:1], v[46:47] op_sel_hi:[1,0,1]
	v_pk_mul_f32 v[46:47], v[70:71], v[84:85] op_sel_hi:[0,1]
	v_pk_fma_f32 v[84:85], v[42:43], v[0:1], v[46:47] op_sel_hi:[1,0,1]
	v_pk_mul_f32 v[42:43], v[70:71], v[86:87] op_sel_hi:[0,1]
	v_pk_fma_f32 v[86:87], v[44:45], v[0:1], v[42:43] op_sel_hi:[1,0,1]
	v_pk_mul_f32 v[42:43], v[70:71], v[88:89] op_sel_hi:[0,1]
	v_pk_fma_f32 v[88:89], v[38:39], v[0:1], v[42:43] op_sel_hi:[1,0,1]
	v_pk_mul_f32 v[38:39], v[70:71], v[90:91] op_sel_hi:[0,1]
	s_add_i32 s18, s18, s25
	s_add_i32 s10, s10, 2
	s_addk_i32 s7, 0x640
	s_cmp_gt_u32 s10, 13
	v_pk_fma_f32 v[90:91], v[40:41], v[0:1], v[38:39] op_sel_hi:[1,0,1]
	s_cbranch_scc0 .LBB0_906

.LBB0_916:
	s_waitcnt lgkmcnt(5)
	v_pk_fma_f32 v[100:101], v[74:75], v[2:3], 0 op_sel_hi:[1,1,0]
	s_waitcnt lgkmcnt(0)
	v_mov_b32_e32 v37, v34
	v_add_u32_e32 v34, s7, v94
	v_pk_fma_f32 v[30:31], v[74:75], v[30:31], 0 op_sel_hi:[1,1,0]
	v_pk_fma_f32 v[100:101], v[78:79], v[4:5], v[100:101]
	ds_read_b128 v[66:69], v34
	ds_read_b128 v[62:65], v34 offset:16
	ds_read_b128 v[58:61], v34 offset:32
	ds_read_b128 v[54:57], v34 offset:48
	ds_read_b128 v[50:53], v34 offset:256
	ds_read_b128 v[46:49], v34 offset:272
	ds_read_b128 v[42:45], v34 offset:288
	ds_read_b128 v[38:41], v34 offset:304
	v_pk_fma_f32 v[30:31], v[78:79], v[32:33], v[30:31]
	v_pk_fma_f32 v[32:33], v[80:81], v[6:7], v[100:101]
	v_pk_fma_f32 v[26:27], v[80:81], v[26:27], v[30:31]
	v_pk_fma_f32 v[30:31], v[82:83], v[8:9], v[32:33]
	v_pk_fma_f32 v[26:27], v[82:83], v[28:29], v[26:27]
	s_waitcnt lgkmcnt(9)
	v_pk_fma_f32 v[28:29], v[84:85], v[14:15], v[30:31]
	v_pk_fma_f32 v[22:23], v[84:85], v[22:23], v[26:27]
	v_pk_fma_f32 v[26:27], v[86:87], v[16:17], v[28:29]
	v_pk_fma_f32 v[22:23], v[86:87], v[24:25], v[22:23]
	s_waitcnt lgkmcnt(8)
	v_pk_fma_f32 v[24:25], v[88:89], v[10:11], v[26:27]
	v_add_u32_e32 v98, s7, v96
	v_mov_b32_e32 v70, s7
	v_pk_fma_f32 v[18:19], v[88:89], v[18:19], v[22:23]
	v_pk_fma_f32 v[22:23], v[90:91], v[12:13], v[24:25]
	ds_read_b32 v0, v98 offset:512
	ds_read_b96 v[70:72], v70 offset:768
	v_pk_fma_f32 v[18:19], v[90:91], v[20:21], v[18:19]
	v_add_f32_e32 v20, v22, v23
	v_add_f32_e32 v18, v18, v19
	s_nop 0
	v_add_f32_dpp v20, v20, v20 quad_perm:[1,0,3,2] row_mask:0xf bank_mask:0xf bound_ctrl:1
	v_add_f32_dpp v19, v18, v18 quad_perm:[1,0,3,2] row_mask:0xf bank_mask:0xf bound_ctrl:1
	s_nop 0
	v_add_f32_dpp v20, v20, v20 quad_perm:[2,3,0,1] row_mask:0xf bank_mask:0xf bound_ctrl:1
	v_fma_f32 v18, -v37, v20, v73
	v_mul_f32_e32 v18, v35, v18
	v_add_f32_dpp v19, v19, v19 quad_perm:[2,3,0,1] row_mask:0xf bank_mask:0xf bound_ctrl:1
	v_mul_f32_e32 v20, v37, v19
	v_pk_fma_f32 v[20:21], v[36:37], v[18:19], v[20:21] op_sel_hi:[1,1,0]
	s_ashr_i32 s17, s16, 31
	v_bfe_u32 v19, v20, 16, 1
	s_lshl_b64 s[10:11], s[16:17], 9
	v_add3_u32 v19, v20, v19, s28
	v_lshl_add_u64 v[20:21], v[92:93], 0, s[10:11]
	global_store_short_d16_hi v[20:21], v19, off
	v_pk_mul_f32 v[20:21], v[74:75], v[36:37] op_sel:[0,1]
	s_nop 0
	v_pk_fma_f32 v[74:75], v[2:3], v[18:19], v[20:21] op_sel_hi:[1,0,1]
	v_pk_mul_f32 v[2:3], v[78:79], v[36:37] op_sel:[0,1]
	s_waitcnt lgkmcnt(9)
	v_pk_fma_f32 v[66:67], v[74:75], v[66:67], 0 op_sel_hi:[1,1,0]
	v_pk_fma_f32 v[78:79], v[4:5], v[18:19], v[2:3] op_sel_hi:[1,0,1]
	v_pk_mul_f32 v[2:3], v[80:81], v[36:37] op_sel:[0,1]
	v_pk_fma_f32 v[66:67], v[78:79], v[68:69], v[66:67]
	v_pk_fma_f32 v[80:81], v[6:7], v[18:19], v[2:3] op_sel_hi:[1,0,1]
	v_pk_mul_f32 v[2:3], v[82:83], v[36:37] op_sel:[0,1]
	s_waitcnt lgkmcnt(8)
	v_pk_fma_f32 v[62:63], v[80:81], v[62:63], v[66:67]
	v_pk_fma_f32 v[82:83], v[8:9], v[18:19], v[2:3] op_sel_hi:[1,0,1]
	v_pk_mul_f32 v[2:3], v[84:85], v[36:37] op_sel:[0,1]
	v_pk_fma_f32 v[62:63], v[82:83], v[64:65], v[62:63]
	v_pk_fma_f32 v[84:85], v[14:15], v[18:19], v[2:3] op_sel_hi:[1,0,1]
	v_pk_mul_f32 v[2:3], v[86:87], v[36:37] op_sel:[0,1]
	s_waitcnt lgkmcnt(7)
	v_pk_fma_f32 v[58:59], v[84:85], v[58:59], v[62:63]
	v_pk_fma_f32 v[86:87], v[16:17], v[18:19], v[2:3] op_sel_hi:[1,0,1]
	v_pk_mul_f32 v[2:3], v[88:89], v[36:37] op_sel:[0,1]
	v_pk_fma_f32 v[58:59], v[86:87], v[60:61], v[58:59]
	v_pk_fma_f32 v[88:89], v[10:11], v[18:19], v[2:3] op_sel_hi:[1,0,1]
	v_pk_mul_f32 v[2:3], v[90:91], v[36:37] op_sel:[0,1]
	s_waitcnt lgkmcnt(6)
	v_pk_fma_f32 v[54:55], v[88:89], v[54:55], v[58:59]
	v_pk_fma_f32 v[90:91], v[12:13], v[18:19], v[2:3] op_sel_hi:[1,0,1]
	ds_read_b128 v[30:33], v34 offset:800
	ds_read_b128 v[26:29], v34 offset:816
	ds_read_b128 v[22:25], v34 offset:832
	ds_read_b128 v[18:21], v34 offset:848
	ds_read_b128 v[2:5], v34 offset:1056
	ds_read_b128 v[6:9], v34 offset:1072
	ds_read_b128 v[14:17], v34 offset:1088
	ds_read_b128 v[10:13], v34 offset:1104
	v_mov_b32_e32 v34, s7
	ds_read_b32 v73, v98 offset:1312
	ds_read_b96 v[34:36], v34 offset:1568
	s_waitcnt lgkmcnt(14)
	v_pk_fma_f32 v[98:99], v[74:75], v[50:51], 0 op_sel_hi:[1,1,0]
	v_pk_fma_f32 v[54:55], v[90:91], v[56:57], v[54:55]
	v_pk_fma_f32 v[98:99], v[78:79], v[52:53], v[98:99]
	s_nop 0
	v_pk_fma_f32 v[68:69], v[80:81], v[46:47], v[98:99]
	s_nop 0
	v_pk_fma_f32 v[66:67], v[82:83], v[48:49], v[68:69]
	s_waitcnt lgkmcnt(13)
	v_pk_fma_f32 v[64:65], v[84:85], v[42:43], v[66:67]
	s_nop 0
	v_pk_fma_f32 v[62:63], v[86:87], v[44:45], v[64:65]
	s_waitcnt lgkmcnt(12)
	v_pk_fma_f32 v[60:61], v[88:89], v[38:39], v[62:63]
	s_nop 0
	v_pk_fma_f32 v[58:59], v[90:91], v[40:41], v[60:61]
	s_nop 0
	v_add_f32_e32 v37, v58, v59
	s_nop 1
	v_add_f32_dpp v37, v37, v37 quad_perm:[1,0,3,2] row_mask:0xf bank_mask:0xf bound_ctrl:1
	s_nop 1
	v_add_f32_dpp v56, v37, v37 quad_perm:[2,3,0,1] row_mask:0xf bank_mask:0xf bound_ctrl:1
	v_add_f32_e32 v37, v54, v55
	s_waitcnt lgkmcnt(10)
	v_fma_f32 v0, -v70, v56, v0
	v_mul_f32_e32 v0, v71, v0
	v_add_f32_dpp v37, v37, v37 quad_perm:[1,0,3,2] row_mask:0xf bank_mask:0xf bound_ctrl:1
	s_nop 1
	v_add_f32_dpp v54, v37, v37 quad_perm:[2,3,0,1] row_mask:0xf bank_mask:0xf bound_ctrl:1
	v_mov_b32_e32 v71, v72
	v_mov_b32_e32 v55, v0
	v_mul_f32_e32 v56, v72, v0
	s_add_i32 s10, s24, s16
	v_pk_fma_f32 v[54:55], v[70:71], v[54:55], v[56:57] op_sel_hi:[1,1,0]
	s_ashr_i32 s11, s10, 31
	v_bfe_u32 v37, v54, 16, 1
	s_lshl_b64 s[10:11], s[10:11], 9
	v_add3_u32 v37, v54, v37, s28
	v_lshl_add_u64 v[54:55], v[92:93], 0, s[10:11]
	global_store_short_d16_hi v[54:55], v37, off
	v_pk_mul_f32 v[54:55], v[70:71], v[74:75] op_sel_hi:[0,1]
	v_pk_fma_f32 v[74:75], v[50:51], v[0:1], v[54:55] op_sel_hi:[1,0,1]
	v_pk_mul_f32 v[50:51], v[70:71], v[78:79] op_sel_hi:[0,1]
	v_pk_fma_f32 v[78:79], v[52:53], v[0:1], v[50:51] op_sel_hi:[1,0,1]
	v_pk_mul_f32 v[50:51], v[70:71], v[80:81] op_sel_hi:[0,1]
	v_pk_fma_f32 v[80:81], v[46:47], v[0:1], v[50:51] op_sel_hi:[1,0,1]
	v_pk_mul_f32 v[46:47], v[70:71], v[82:83] op_sel_hi:[0,1]
	v_pk_fma_f32 v[82:83], v[48:49], v[0:1], v[46:47] op_sel_hi:[1,0,1]
	v_pk_mul_f32 v[46:47], v[70:71], v[84:85] op_sel_hi:[0,1]
	v_pk_fma_f32 v[84:85], v[42:43], v[0:1], v[46:47] op_sel_hi:[1,0,1]
	v_pk_mul_f32 v[42:43], v[70:71], v[86:87] op_sel_hi:[0,1]
	v_pk_fma_f32 v[86:87], v[44:45], v[0:1], v[42:43] op_sel_hi:[1,0,1]
	v_pk_mul_f32 v[42:43], v[70:71], v[88:89] op_sel_hi:[0,1]
	v_pk_fma_f32 v[88:89], v[38:39], v[0:1], v[42:43] op_sel_hi:[1,0,1]
	v_pk_mul_f32 v[38:39], v[70:71], v[90:91] op_sel_hi:[0,1]
	s_add_i32 s16, s16, s25
	s_add_i32 s6, s6, 2
	s_addk_i32 s7, 0x640
	v_pk_fma_f32 v[90:91], v[40:41], v[0:1], v[38:39] op_sel_hi:[1,0,1]
	s_waitcnt lgkmcnt(5)
	v_pk_fma_f32 v[100:101], v[74:75], v[2:3], 0 op_sel_hi:[1,1,0]
	s_waitcnt lgkmcnt(0)
	v_mov_b32_e32 v37, v34
	v_add_u32_e32 v34, s7, v94
	v_pk_fma_f32 v[30:31], v[74:75], v[30:31], 0 op_sel_hi:[1,1,0]
	v_pk_fma_f32 v[100:101], v[78:79], v[4:5], v[100:101]
	ds_read_b128 v[66:69], v34
	ds_read_b128 v[62:65], v34 offset:16
	ds_read_b128 v[58:61], v34 offset:32
	ds_read_b128 v[54:57], v34 offset:48
	ds_read_b128 v[50:53], v34 offset:256
	ds_read_b128 v[46:49], v34 offset:272
	ds_read_b128 v[42:45], v34 offset:288
	ds_read_b128 v[38:41], v34 offset:304
	v_pk_fma_f32 v[30:31], v[78:79], v[32:33], v[30:31]
	v_pk_fma_f32 v[32:33], v[80:81], v[6:7], v[100:101]
	v_pk_fma_f32 v[26:27], v[80:81], v[26:27], v[30:31]
	v_pk_fma_f32 v[30:31], v[82:83], v[8:9], v[32:33]
	v_pk_fma_f32 v[26:27], v[82:83], v[28:29], v[26:27]
	s_waitcnt lgkmcnt(9)
	v_pk_fma_f32 v[28:29], v[84:85], v[14:15], v[30:31]
	v_pk_fma_f32 v[22:23], v[84:85], v[22:23], v[26:27]
	v_pk_fma_f32 v[26:27], v[86:87], v[16:17], v[28:29]
	v_pk_fma_f32 v[22:23], v[86:87], v[24:25], v[22:23]
	s_waitcnt lgkmcnt(8)
	v_pk_fma_f32 v[24:25], v[88:89], v[10:11], v[26:27]
	v_add_u32_e32 v98, s7, v96
	v_mov_b32_e32 v70, s7
	v_pk_fma_f32 v[18:19], v[88:89], v[18:19], v[22:23]
	v_pk_fma_f32 v[22:23], v[90:91], v[12:13], v[24:25]
	ds_read_b32 v0, v98 offset:512
	ds_read_b96 v[70:72], v70 offset:768
	v_pk_fma_f32 v[18:19], v[90:91], v[20:21], v[18:19]
	v_add_f32_e32 v20, v22, v23
	v_add_f32_e32 v18, v18, v19
	s_nop 0
	v_add_f32_dpp v20, v20, v20 quad_perm:[1,0,3,2] row_mask:0xf bank_mask:0xf bound_ctrl:1
	v_add_f32_dpp v19, v18, v18 quad_perm:[1,0,3,2] row_mask:0xf bank_mask:0xf bound_ctrl:1
	s_nop 0
	v_add_f32_dpp v20, v20, v20 quad_perm:[2,3,0,1] row_mask:0xf bank_mask:0xf bound_ctrl:1
	v_fma_f32 v18, -v37, v20, v73
	v_mul_f32_e32 v18, v35, v18
	v_add_f32_dpp v19, v19, v19 quad_perm:[2,3,0,1] row_mask:0xf bank_mask:0xf bound_ctrl:1
	v_mul_f32_e32 v20, v37, v19
	v_pk_fma_f32 v[20:21], v[36:37], v[18:19], v[20:21] op_sel_hi:[1,1,0]
	s_ashr_i32 s17, s16, 31
	v_bfe_u32 v19, v20, 16, 1
	s_lshl_b64 s[10:11], s[16:17], 9
	v_add3_u32 v19, v20, v19, s28
	v_lshl_add_u64 v[20:21], v[92:93], 0, s[10:11]
	global_store_short_d16_hi v[20:21], v19, off
	v_pk_mul_f32 v[20:21], v[74:75], v[36:37] op_sel:[0,1]
	s_nop 0
	v_pk_fma_f32 v[74:75], v[2:3], v[18:19], v[20:21] op_sel_hi:[1,0,1]
	v_pk_mul_f32 v[2:3], v[78:79], v[36:37] op_sel:[0,1]
	s_waitcnt lgkmcnt(9)
	v_pk_fma_f32 v[66:67], v[74:75], v[66:67], 0 op_sel_hi:[1,1,0]
	v_pk_fma_f32 v[78:79], v[4:5], v[18:19], v[2:3] op_sel_hi:[1,0,1]
	v_pk_mul_f32 v[2:3], v[80:81], v[36:37] op_sel:[0,1]
	v_pk_fma_f32 v[66:67], v[78:79], v[68:69], v[66:67]
	v_pk_fma_f32 v[80:81], v[6:7], v[18:19], v[2:3] op_sel_hi:[1,0,1]
	v_pk_mul_f32 v[2:3], v[82:83], v[36:37] op_sel:[0,1]
	s_waitcnt lgkmcnt(8)
	v_pk_fma_f32 v[62:63], v[80:81], v[62:63], v[66:67]
	v_pk_fma_f32 v[82:83], v[8:9], v[18:19], v[2:3] op_sel_hi:[1,0,1]
	v_pk_mul_f32 v[2:3], v[84:85], v[36:37] op_sel:[0,1]
	v_pk_fma_f32 v[62:63], v[82:83], v[64:65], v[62:63]
	v_pk_fma_f32 v[84:85], v[14:15], v[18:19], v[2:3] op_sel_hi:[1,0,1]
	v_pk_mul_f32 v[2:3], v[86:87], v[36:37] op_sel:[0,1]
	s_waitcnt lgkmcnt(7)
	v_pk_fma_f32 v[58:59], v[84:85], v[58:59], v[62:63]
	v_pk_fma_f32 v[86:87], v[16:17], v[18:19], v[2:3] op_sel_hi:[1,0,1]
	v_pk_mul_f32 v[2:3], v[88:89], v[36:37] op_sel:[0,1]
	v_pk_fma_f32 v[58:59], v[86:87], v[60:61], v[58:59]
	v_pk_fma_f32 v[88:89], v[10:11], v[18:19], v[2:3] op_sel_hi:[1,0,1]
	v_pk_mul_f32 v[2:3], v[90:91], v[36:37] op_sel:[0,1]
	s_waitcnt lgkmcnt(6)
	v_pk_fma_f32 v[54:55], v[88:89], v[54:55], v[58:59]
	v_pk_fma_f32 v[90:91], v[12:13], v[18:19], v[2:3] op_sel_hi:[1,0,1]
	ds_read_b128 v[30:33], v34 offset:800
	ds_read_b128 v[26:29], v34 offset:816
	ds_read_b128 v[22:25], v34 offset:832
	ds_read_b128 v[18:21], v34 offset:848
	ds_read_b128 v[2:5], v34 offset:1056
	ds_read_b128 v[6:9], v34 offset:1072
	ds_read_b128 v[14:17], v34 offset:1088
	ds_read_b128 v[10:13], v34 offset:1104
	v_mov_b32_e32 v34, s7
	ds_read_b32 v73, v98 offset:1312
	ds_read_b96 v[34:36], v34 offset:1568
	s_waitcnt lgkmcnt(14)
	v_pk_fma_f32 v[98:99], v[74:75], v[50:51], 0 op_sel_hi:[1,1,0]
	v_pk_fma_f32 v[54:55], v[90:91], v[56:57], v[54:55]
	v_pk_fma_f32 v[98:99], v[78:79], v[52:53], v[98:99]
	s_nop 0
	v_pk_fma_f32 v[68:69], v[80:81], v[46:47], v[98:99]
	s_nop 0
	v_pk_fma_f32 v[66:67], v[82:83], v[48:49], v[68:69]
	s_waitcnt lgkmcnt(13)
	v_pk_fma_f32 v[64:65], v[84:85], v[42:43], v[66:67]
	s_nop 0
	v_pk_fma_f32 v[62:63], v[86:87], v[44:45], v[64:65]
	s_waitcnt lgkmcnt(12)
	v_pk_fma_f32 v[60:61], v[88:89], v[38:39], v[62:63]
	s_nop 0
	v_pk_fma_f32 v[58:59], v[90:91], v[40:41], v[60:61]
	s_nop 0
	v_add_f32_e32 v37, v58, v59
	s_nop 1
	v_add_f32_dpp v37, v37, v37 quad_perm:[1,0,3,2] row_mask:0xf bank_mask:0xf bound_ctrl:1
	s_nop 1
	v_add_f32_dpp v56, v37, v37 quad_perm:[2,3,0,1] row_mask:0xf bank_mask:0xf bound_ctrl:1
	v_add_f32_e32 v37, v54, v55
	s_waitcnt lgkmcnt(10)
	v_fma_f32 v0, -v70, v56, v0
	v_mul_f32_e32 v0, v71, v0
	v_add_f32_dpp v37, v37, v37 quad_perm:[1,0,3,2] row_mask:0xf bank_mask:0xf bound_ctrl:1
	s_nop 1
	v_add_f32_dpp v54, v37, v37 quad_perm:[2,3,0,1] row_mask:0xf bank_mask:0xf bound_ctrl:1
	v_mov_b32_e32 v71, v72
	v_mov_b32_e32 v55, v0
	v_mul_f32_e32 v56, v72, v0
	s_add_i32 s10, s24, s16
	v_pk_fma_f32 v[54:55], v[70:71], v[54:55], v[56:57] op_sel_hi:[1,1,0]
	s_ashr_i32 s11, s10, 31
	v_bfe_u32 v37, v54, 16, 1
	s_lshl_b64 s[10:11], s[10:11], 9
	v_add3_u32 v37, v54, v37, s28
	v_lshl_add_u64 v[54:55], v[92:93], 0, s[10:11]
	global_store_short_d16_hi v[54:55], v37, off
	v_pk_mul_f32 v[54:55], v[70:71], v[74:75] op_sel_hi:[0,1]
	v_pk_fma_f32 v[74:75], v[50:51], v[0:1], v[54:55] op_sel_hi:[1,0,1]
	v_pk_mul_f32 v[50:51], v[70:71], v[78:79] op_sel_hi:[0,1]
	v_pk_fma_f32 v[78:79], v[52:53], v[0:1], v[50:51] op_sel_hi:[1,0,1]
	v_pk_mul_f32 v[50:51], v[70:71], v[80:81] op_sel_hi:[0,1]
	v_pk_fma_f32 v[80:81], v[46:47], v[0:1], v[50:51] op_sel_hi:[1,0,1]
	v_pk_mul_f32 v[46:47], v[70:71], v[82:83] op_sel_hi:[0,1]
	v_pk_fma_f32 v[82:83], v[48:49], v[0:1], v[46:47] op_sel_hi:[1,0,1]
	v_pk_mul_f32 v[46:47], v[70:71], v[84:85] op_sel_hi:[0,1]
	v_pk_fma_f32 v[84:85], v[42:43], v[0:1], v[46:47] op_sel_hi:[1,0,1]
	v_pk_mul_f32 v[42:43], v[70:71], v[86:87] op_sel_hi:[0,1]
	v_pk_fma_f32 v[86:87], v[44:45], v[0:1], v[42:43] op_sel_hi:[1,0,1]
	v_pk_mul_f32 v[42:43], v[70:71], v[88:89] op_sel_hi:[0,1]
	v_pk_fma_f32 v[88:89], v[38:39], v[0:1], v[42:43] op_sel_hi:[1,0,1]
	v_pk_mul_f32 v[38:39], v[70:71], v[90:91] op_sel_hi:[0,1]
	s_add_i32 s16, s16, s25
	s_add_i32 s6, s6, 2
	s_addk_i32 s7, 0x640
	s_cmp_gt_u32 s6, 13
	v_pk_fma_f32 v[90:91], v[40:41], v[0:1], v[38:39] op_sel_hi:[1,0,1]
	s_cbranch_scc0 .LBB0_916
	s_branch .LBB0_899
